# ret_scan: 40 waits that a per-block counter bound proves redundant and 6 pads left in front of rsq removed (checked with the wait-state checker)
# baseline (speedup 1.0000x reference)
.LBB0_190:
	v_lshl_add_u32 v81, v83, 2, v147
	s_waitcnt lgkmcnt(0)
	s_barrier
	ds_read_b128 v[170:173], v81
	ds_read_b128 v[174:177], v81 offset:256
	ds_read_b128 v[178:181], v81 offset:512
	ds_read_b128 v[182:185], v81 offset:768
	ds_read_b128 v[186:189], v81 offset:1024
	ds_read_b128 v[190:193], v81 offset:1280
	ds_read_b128 v[194:197], v81 offset:1536
	ds_read_b128 v[198:201], v81 offset:1792
	ds_read_b128 v[212:215], v81 offset:64
	ds_read_b128 v[216:219], v81 offset:320
	ds_read_b128 v[220:223], v81 offset:576
	ds_read_b128 v[224:227], v81 offset:832
	ds_read_b128 v[228:231], v81 offset:1088
	ds_read_b128 v[232:235], v81 offset:1344
	ds_read_b128 v[236:239], v81 offset:1600
	ds_read_b128 v[240:243], v81 offset:1856
	s_mov_b32 s4, 0xa180000
	v_lshl_add_u64 v[88:89], v[88:89], 0, s[82:83]
	v_lshl_add_u64 v[86:87], v[86:87], 0, s[82:83]
	v_lshl_add_u64 v[90:91], v[90:91], 0, s[82:83]
	s_waitcnt lgkmcnt(14)
	v_pk_add_f32 v[72:73], v[172:173], v[176:177]
	v_pk_add_f32 v[70:71], v[170:171], v[174:175]
	v_lshl_add_u64 v[92:93], v[92:93], 0, s[74:75]
	s_mov_b32 s22, s23
	s_waitcnt lgkmcnt(13)
	v_pk_add_f32 v[72:73], v[72:73], v[180:181]
	v_pk_add_f32 v[70:71], v[70:71], v[178:179]
	s_waitcnt lgkmcnt(12)
	v_pk_add_f32 v[72:73], v[72:73], v[184:185]
	v_pk_add_f32 v[70:71], v[70:71], v[182:183]
	s_waitcnt lgkmcnt(11)
	v_pk_add_f32 v[72:73], v[72:73], v[188:189]
	v_pk_add_f32 v[70:71], v[70:71], v[186:187]
	s_waitcnt lgkmcnt(10)
	v_pk_add_f32 v[72:73], v[72:73], v[192:193]
	v_pk_add_f32 v[70:71], v[70:71], v[190:191]
	s_waitcnt lgkmcnt(9)
	v_pk_add_f32 v[72:73], v[72:73], v[196:197]
	v_pk_add_f32 v[70:71], v[70:71], v[194:195]
	s_waitcnt lgkmcnt(8)
	v_pk_add_f32 v[66:67], v[70:71], v[198:199]
	s_nop 0
	v_fmamk_f32 v66, v66, 0x3c000000, v169
	v_pk_add_f32 v[68:69], v[72:73], v[200:201]
	v_rsq_f32_e32 v66, v66
	s_nop 0
	v_mul_f32_e32 v62, v62, v66
	v_lshlrev_b32_e32 v66, 2, v121
	v_mul_lo_u32 v70, v120, s62
	v_add3_u32 v70, v115, v66, v70
	v_fmamk_f32 v66, v67, 0x3c000000, v169
	v_rsq_f32_e32 v66, v66
	s_nop 0
	v_mul_f32_e32 v63, v63, v66
	v_add_u32_e32 v66, 0x4200, v70
	ds_write2_b32 v66, v62, v63 offset1:132
	v_fmamk_f32 v62, v68, 0x3c000000, v169
	v_rsq_f32_e32 v62, v62
	s_nop 0
	v_fmamk_f32 v63, v69, 0x3c000000, v169
	v_mul_f32_e32 v62, v64, v62
	s_nop 0
	v_rsq_f32_e32 v63, v63
	s_nop 0
	v_mul_f32_e32 v63, v65, v63
	v_add_u32_e32 v64, 0x4600, v70
	ds_write2_b32 v64, v62, v63 offset0:8 offset1:140
	s_waitcnt lgkmcnt(8)
	v_pk_add_f32 v[68:69], v[214:215], v[218:219]
	v_pk_add_f32 v[66:67], v[212:213], v[216:217]
	s_waitcnt lgkmcnt(7)
	v_pk_add_f32 v[68:69], v[68:69], v[222:223]
	v_pk_add_f32 v[66:67], v[66:67], v[220:221]
	s_waitcnt lgkmcnt(6)
	v_pk_add_f32 v[68:69], v[68:69], v[226:227]
	v_pk_add_f32 v[66:67], v[66:67], v[224:225]
	s_waitcnt lgkmcnt(5)
	v_pk_add_f32 v[68:69], v[68:69], v[230:231]
	v_pk_add_f32 v[66:67], v[66:67], v[228:229]
	s_waitcnt lgkmcnt(4)
	v_pk_add_f32 v[68:69], v[68:69], v[234:235]
	v_pk_add_f32 v[66:67], v[66:67], v[232:233]
	s_waitcnt lgkmcnt(3)
	v_pk_add_f32 v[68:69], v[68:69], v[238:239]
	v_pk_add_f32 v[66:67], v[66:67], v[236:237]
	s_waitcnt lgkmcnt(2)
	v_pk_add_f32 v[62:63], v[66:67], v[240:241]
	s_nop 0
	v_fmamk_f32 v62, v62, 0x3c000000, v169
	v_pk_add_f32 v[64:65], v[68:69], v[242:243]
	v_rsq_f32_e32 v62, v62
	s_cmp_lt_u32 s22, 30
	s_cbranch_scc0 .Lrv_c2_n0
	s_waitcnt vmcnt(4)
	s_branch .Lrv_c2_end

.Lrv_c2_end:
	v_and_b32_e32 v67, 0xffff0000, v46
	v_mul_f32_e32 v58, v58, v62
	v_fmamk_f32 v62, v63, 0x3c000000, v169
	v_lshlrev_b32_e32 v66, 16, v46
	v_rsq_f32_e32 v62, v62
	s_nop 0
	v_mul_f32_e32 v59, v59, v62
	v_add_u32_e32 v62, 0x6200, v70
	ds_write2_b32 v62, v58, v59 offset0:64 offset1:196
	v_fmamk_f32 v58, v64, 0x3c000000, v169
	v_rsq_f32_e32 v58, v58
	s_nop 0
	v_fmamk_f32 v59, v65, 0x3c000000, v169
	v_mul_f32_e32 v58, v60, v58
	s_nop 0
	v_rsq_f32_e32 v59, v59
	s_nop 0
	v_mul_f32_e32 v59, v61, v59
	v_add_u32_e32 v60, 0x6600, v70
	ds_write2_b32 v60, v58, v59 offset0:72 offset1:204
	ds_read_b128 v[58:61], v113
	ds_read_b128 v[62:65], v113 offset:16
	s_waitcnt lgkmcnt(1)
	v_pk_mul_f32 v[58:59], v[58:59], v[66:67]
	s_nop 0
	v_cvt_pk_bf16_f32 v46, v58, v59
	v_lshlrev_b32_e32 v58, 16, v47
	v_and_b32_e32 v59, 0xffff0000, v47
	v_pk_mul_f32 v[58:59], v[60:61], v[58:59]
	s_nop 0
	v_cvt_pk_bf16_f32 v47, v58, v59
	v_lshlrev_b32_e32 v58, 16, v48
	v_and_b32_e32 v59, 0xffff0000, v48
	s_waitcnt lgkmcnt(0)
	v_pk_mul_f32 v[58:59], v[62:63], v[58:59]
	s_nop 0
	v_cvt_pk_bf16_f32 v48, v58, v59
	v_lshlrev_b32_e32 v58, 16, v49
	v_and_b32_e32 v59, 0xffff0000, v49
	v_pk_mul_f32 v[58:59], v[64:65], v[58:59]
	s_nop 0
	v_cvt_pk_bf16_f32 v49, v58, v59
	v_add_co_u32_e32 v58, vcc, s4, v96
	s_nop 1
	v_addc_co_u32_e32 v59, vcc, 0, v97, vcc
	s_andn2_b64 vcc, exec, s[48:49]
	global_store_dwordx4 v[58:59], v[46:49], off
	s_cbranch_vccz .LBB0_271

; #define RET_LOAD(X, nn) do { const bf16_t* r_ = gsrc + (size_t)(nn) * 64 * 1536; X[0] = *(const u32x4*)(r_ + h * 64 + ld0); X[1] = *(const u32x4*)(r_ + 256 + h * 64 + ld0); \
;         X[2] = *(const u32x4*)(r_ + 512 + h * 128 + lc0); X[3] = *(const u32x4*)(r_ + 512 + h * 128 + lc0 + 8); } while (0)
; #define RET_STORE(X, bufi) do { bf16_t* B_ = (bf16_t*)(lds + (bufi) * RB); *(u32x4*)(B_ + li * 72 + ld0) = X[0]; *(u32x4*)(B_ + 64 * 72 + li * 72 + ld0) = X[1]; \
;         *(u32x4*)(B_ + 128 * 72 + li * 136 + lc0) = X[2]; *(u32x4*)(B_ + 128 * 72 + li * 136 + lc0 + 8) = X[3]; } while (0)
; DI void ret_scan_wg(const Params& p, int l, int bhi, unsigned char* lds, int tid) {
;     ...
;     u32x4 stA[4], stB[4];
;     RET_LOAD(stA, 0); RET_LOAD(stB, 1); RET_STORE(stA, 0); RET_STORE(stB, 1); RET_LOAD(stA, 2);
;     __syncthreads();
;     RET_PTILE(0);
;     __syncthreads();
.LBB0_199:
	s_or_b64 exec, exec, s[48:49]
	s_mul_i32 s4, s22, 0xab
	s_bfe_u32 s4, s4, 0x70009
	s_mul_i32 s4, s4, 3
	s_sub_i32 s4, s22, s4
	v_cvt_pk_bf16_f32 v58, v58, v59
	v_cvt_pk_bf16_f32 v59, v60, v61
	s_and_b32 s4, s4, 0xff
	ds_write_b64 v116, v[58:59]
	v_ashrrev_i32_e32 v58, 2, v97
	v_lshlrev_b32_e32 v83, 2, v96
	s_mul_i32 s4, s4, 0x8c00
	v_add_u32_e32 v119, v58, v83
	v_lshlrev_b32_e32 v58, 3, v97
	v_add_u32_e32 v62, s4, v168
	v_and_b32_e32 v58, 24, v58
	v_mul_lo_u32 v59, v119, s65
	v_add_u32_e32 v132, v62, v58
	v_add3_u32 v58, v132, v118, v59
	v_lshl_add_u32 v134, v96, 3, v62
	v_add_u32_e32 v62, v144, v108
	ds_read_b64_tr_b16 v[136:137], v58 offset:18432
	ds_read_b64_tr_b16 v[138:139], v58 offset:22784
	ds_read_b64_tr_b16 v[152:153], v58 offset:27136
	ds_read_b64_tr_b16 v[154:155], v58 offset:31488
	ds_read_b128 v[156:159], v62
	v_add_u32_e32 v140, s45, v97
	v_mad_u64_u32 v[160:161], s[4:5], v140, s56, v[134:135]
	ds_read2_b64 v[170:173], v160 offset1:4
	ds_read2_b64 v[174:177], v160 offset0:8 offset1:12
	v_add_u32_e32 v141, v144, v114
	ds_read_b128 v[178:181], v141 offset:1024
	ds_read_b128 v[182:185], v141
	v_add_u32_e32 v142, s43, v97
	v_mad_u64_u32 v[162:163], s[4:5], v142, s56, v[134:135]
	ds_read2_b64 v[186:189], v162 offset1:4
	ds_read2_b64 v[190:193], v162 offset0:8 offset1:12
	v_mad_u64_u32 v[194:195], s[4:5], v119, s56, v[132:133]
	ds_read_b64_tr_b16 v[196:197], v194 offset:9216
	ds_read_b64_tr_b16 v[200:201], v194 offset:9248
	ds_read_b64_tr_b16 v[198:199], v194 offset:11520
	ds_read_b64_tr_b16 v[212:213], v194 offset:13824
	ds_read_b64_tr_b16 v[214:215], v194 offset:16128
	ds_read_b64_tr_b16 v[202:203], v194 offset:11552
	ds_read_b64_tr_b16 v[216:217], v194 offset:13856
	ds_read_b64_tr_b16 v[218:219], v194 offset:16160
	ds_read_b64_tr_b16 v[220:221], v194 offset:9280
	ds_read_b64_tr_b16 v[222:223], v194 offset:11584
	ds_read_b64_tr_b16 v[224:225], v194 offset:13888
	ds_read_b64_tr_b16 v[226:227], v194 offset:16192
	ds_read_b64_tr_b16 v[228:229], v194 offset:9312
	ds_read_b64_tr_b16 v[230:231], v194 offset:11616
	ds_read_b64_tr_b16 v[232:233], v194 offset:13920
	ds_read_b64_tr_b16 v[234:235], v194 offset:16224
	s_waitcnt lgkmcnt(15)
	v_mfma_f32_16x16x32_bf16 v[62:65], v[156:159], v[136:139], v[0:3]
	v_cvt_pk_bf16_f32 v58, v50, v51
	v_cvt_pk_bf16_f32 v59, v52, v53
	v_cvt_pk_bf16_f32 v60, v38, v39
	v_cvt_pk_bf16_f32 v61, v40, v41
	v_cvt_pk_bf16_f32 v120, v42, v43
	v_cvt_pk_bf16_f32 v121, v44, v45
	v_mfma_f32_16x16x32_bf16 v[62:65], v[170:173], v[58:61], v[62:65]
	v_cvt_pk_bf16_f32 v122, v54, v55
	v_cvt_pk_bf16_f32 v123, v56, v57
	s_nop 1
	v_mfma_f32_16x16x32_bf16 v[62:65], v[174:177], v[120:123], v[62:65]
	v_mfma_f32_16x16x32_bf16 v[124:127], v[182:185], v[136:139], v[0:3]
	v_mov_b32_e32 v81, v80
	v_pk_mul_f32 v[52:53], v[80:81], v[52:53]
	v_pk_mul_f32 v[50:51], v[84:85], v[50:51]
	v_mfma_f32_16x16x32_bf16 v[124:127], v[178:181], v[152:155], v[124:127]
	v_pk_mul_f32 v[40:41], v[80:81], v[40:41]
	v_pk_mul_f32 v[38:39], v[84:85], v[38:39]
	v_mfma_f32_16x16x32_bf16 v[58:61], v[186:189], v[58:61], v[124:127]
	s_nop 2
	v_mfma_f32_16x16x32_bf16 v[58:61], v[190:193], v[120:123], v[58:61]
	v_pk_mul_f32 v[44:45], v[80:81], v[44:45]
	v_pk_mul_f32 v[42:43], v[84:85], v[42:43]
	s_waitcnt lgkmcnt(13)
	v_mfma_f32_16x16x32_bf16 v[50:53], v[196:199], v[136:139], v[50:53]
	v_pk_mul_f32 v[56:57], v[80:81], v[56:57]
	s_waitcnt lgkmcnt(11)
	v_mfma_f32_16x16x32_bf16 v[50:53], v[212:215], v[152:155], v[50:53]
	v_pk_mul_f32 v[54:55], v[84:85], v[54:55]
	v_cmp_eq_u32_e32 vcc, 0, v97
	s_waitcnt lgkmcnt(10)
	v_mfma_f32_16x16x32_bf16 v[38:41], v[200:203], v[136:139], v[38:41]
	s_waitcnt lgkmcnt(8)
	v_mfma_f32_16x16x32_bf16 v[38:41], v[216:219], v[152:155], v[38:41]
	s_waitcnt lgkmcnt(6)
	v_mfma_f32_16x16x32_bf16 v[42:45], v[220:223], v[136:139], v[42:45]
	s_waitcnt lgkmcnt(4)
	v_mfma_f32_16x16x32_bf16 v[42:45], v[224:227], v[152:155], v[42:45]
	s_waitcnt lgkmcnt(2)
	v_mfma_f32_16x16x32_bf16 v[54:57], v[228:231], v[136:139], v[54:57]
	s_waitcnt lgkmcnt(0)
	v_mfma_f32_16x16x32_bf16 v[54:57], v[232:235], v[152:155], v[54:57]
	v_mul_f32_e32 v170, v62, v62
	v_mul_f32_e32 v171, v63, v63
	v_mul_f32_e32 v172, v64, v64
	v_mul_f32_e32 v173, v65, v65
	v_mul_f32_e32 v174, v58, v58
	v_mul_f32_e32 v175, v59, v59
	v_mul_f32_e32 v176, v60, v60
	v_mul_f32_e32 v177, v61, v61
	v_add_u32_e32 v66, v83, v112
	v_lshl_add_u32 v66, v66, 2, v143
	v_mov_b32_dpp v178, v170 quad_perm:[1,0,3,2] row_mask:0xf bank_mask:0xf
	v_mov_b32_dpp v179, v171 quad_perm:[1,0,3,2] row_mask:0xf bank_mask:0xf
	v_mov_b32_dpp v180, v172 quad_perm:[1,0,3,2] row_mask:0xf bank_mask:0xf
	v_mov_b32_dpp v181, v173 quad_perm:[1,0,3,2] row_mask:0xf bank_mask:0xf
	v_mov_b32_dpp v182, v174 quad_perm:[1,0,3,2] row_mask:0xf bank_mask:0xf
	v_mov_b32_dpp v183, v175 quad_perm:[1,0,3,2] row_mask:0xf bank_mask:0xf
	v_mov_b32_dpp v184, v176 quad_perm:[1,0,3,2] row_mask:0xf bank_mask:0xf
	v_mov_b32_dpp v185, v177 quad_perm:[1,0,3,2] row_mask:0xf bank_mask:0xf
	v_fmac_f32_e32 v178, v62, v62
	v_fmac_f32_e32 v179, v63, v63
	v_fmac_f32_e32 v180, v64, v64
	v_fmac_f32_e32 v181, v65, v65
	v_fmac_f32_e32 v182, v58, v58
	v_fmac_f32_e32 v183, v59, v59
	v_fmac_f32_e32 v184, v60, v60
	v_fmac_f32_e32 v185, v61, v61
	v_add_f32_dpp v170, v178, v178 quad_perm:[2,3,0,1] row_mask:0xf bank_mask:0xf bound_ctrl:1
	v_add_f32_dpp v171, v179, v179 quad_perm:[2,3,0,1] row_mask:0xf bank_mask:0xf bound_ctrl:1
	v_add_f32_dpp v172, v180, v180 quad_perm:[2,3,0,1] row_mask:0xf bank_mask:0xf bound_ctrl:1
	v_add_f32_dpp v173, v181, v181 quad_perm:[2,3,0,1] row_mask:0xf bank_mask:0xf bound_ctrl:1
	v_add_f32_dpp v174, v182, v182 quad_perm:[2,3,0,1] row_mask:0xf bank_mask:0xf bound_ctrl:1
	v_add_f32_dpp v175, v183, v183 quad_perm:[2,3,0,1] row_mask:0xf bank_mask:0xf bound_ctrl:1
	v_add_f32_dpp v176, v184, v184 quad_perm:[2,3,0,1] row_mask:0xf bank_mask:0xf bound_ctrl:1
	v_add_f32_dpp v177, v185, v185 quad_perm:[2,3,0,1] row_mask:0xf bank_mask:0xf bound_ctrl:1
	v_add_f32_dpp v170, v170, v170 row_half_mirror row_mask:0xf bank_mask:0xf bound_ctrl:1
	v_add_f32_dpp v171, v171, v171 row_half_mirror row_mask:0xf bank_mask:0xf bound_ctrl:1
	v_add_f32_dpp v172, v172, v172 row_half_mirror row_mask:0xf bank_mask:0xf bound_ctrl:1
	v_add_f32_dpp v173, v173, v173 row_half_mirror row_mask:0xf bank_mask:0xf bound_ctrl:1
	v_add_f32_dpp v174, v174, v174 row_half_mirror row_mask:0xf bank_mask:0xf bound_ctrl:1
	v_add_f32_dpp v175, v175, v175 row_half_mirror row_mask:0xf bank_mask:0xf bound_ctrl:1
	v_add_f32_dpp v176, v176, v176 row_half_mirror row_mask:0xf bank_mask:0xf bound_ctrl:1
	v_add_f32_dpp v177, v177, v177 row_half_mirror row_mask:0xf bank_mask:0xf bound_ctrl:1
	v_mov_b32_dpp v178, v170 row_mirror row_mask:0xf bank_mask:0xf
	v_mov_b32_dpp v179, v171 row_mirror row_mask:0xf bank_mask:0xf
	v_mov_b32_dpp v180, v172 row_mirror row_mask:0xf bank_mask:0xf
	v_mov_b32_dpp v181, v173 row_mirror row_mask:0xf bank_mask:0xf
	v_mov_b32_dpp v182, v174 row_mirror row_mask:0xf bank_mask:0xf
	v_mov_b32_dpp v183, v175 row_mirror row_mask:0xf bank_mask:0xf
	v_mov_b32_dpp v184, v176 row_mirror row_mask:0xf bank_mask:0xf
	v_mov_b32_dpp v185, v177 row_mirror row_mask:0xf bank_mask:0xf
	s_and_saveexec_b64 s[4:5], vcc
	v_add_f32_e32 v170, v170, v178
	v_add_f32_e32 v171, v171, v179
	v_add_f32_e32 v172, v172, v180
	v_add_f32_e32 v173, v173, v181
	v_add_f32_e32 v174, v174, v182
	v_add_f32_e32 v175, v175, v183
	v_add_f32_e32 v176, v176, v184
	v_add_f32_e32 v177, v177, v185
	ds_write_b32 v66, v170
	ds_write_b32 v66, v171 offset:4
	ds_write_b32 v66, v172 offset:8
	ds_write_b32 v66, v173 offset:12
	ds_write_b32 v66, v174 offset:64
	ds_write_b32 v66, v175 offset:68
	ds_write_b32 v66, v176 offset:72
	ds_write_b32 v66, v177 offset:76
	s_or_b64 exec, exec, s[4:5]
	s_add_i32 s23, s22, 2
	s_cmp_lt_u32 s22, 30
	s_cselect_b64 s[50:51], -1, 0
	s_cmp_gt_u32 s22, 29
	s_cselect_b64 s[48:49], -1, 0
	s_and_b64 vcc, exec, s[48:49]
	v_lshlrev_b32_e32 v119, 1, v164
	s_cbranch_vccnz .LBB0_217
	s_mul_i32 s4, s23, 0xab
	s_bfe_u32 s4, s4, 0x70009
	s_mul_i32 s4, s4, 3
	s_sub_i32 s4, s23, s4
	s_and_b32 s4, s4, 0xff
	s_mul_i32 s4, s4, 0x8c00
	v_add_u32_e32 v66, s4, v76
	v_lshl_add_u32 v67, v106, 1, v66
	v_add3_u32 v66, v66, v77, v119
	s_cmp_eq_u32 s22, 0
	s_cbranch_scc0 .Lrv_b1_n0
	s_waitcnt vmcnt(4)
	s_branch .Lrv_b1_end

.LBB0_217:
	v_lshl_add_u32 v81, v83, 2, v143
	s_waitcnt lgkmcnt(0)
	s_barrier
	ds_read_b128 v[170:173], v81
	ds_read_b128 v[174:177], v81 offset:256
	ds_read_b128 v[178:181], v81 offset:512
	ds_read_b128 v[182:185], v81 offset:768
	ds_read_b128 v[186:189], v81 offset:1024
	ds_read_b128 v[190:193], v81 offset:1280
	ds_read_b128 v[194:197], v81 offset:1536
	ds_read_b128 v[198:201], v81 offset:1792
	ds_read_b128 v[212:215], v81 offset:64
	ds_read_b128 v[216:219], v81 offset:320
	ds_read_b128 v[220:223], v81 offset:576
	ds_read_b128 v[224:227], v81 offset:832
	ds_read_b128 v[228:231], v81 offset:1088
	ds_read_b128 v[232:235], v81 offset:1344
	ds_read_b128 v[236:239], v81 offset:1600
	ds_read_b128 v[240:243], v81 offset:1856
	s_waitcnt lgkmcnt(14)
	v_pk_add_f32 v[72:73], v[172:173], v[176:177]
	v_pk_add_f32 v[70:71], v[170:171], v[174:175]
	s_waitcnt lgkmcnt(13)
	v_pk_add_f32 v[72:73], v[72:73], v[180:181]
	v_pk_add_f32 v[70:71], v[70:71], v[178:179]
	s_waitcnt lgkmcnt(12)
	v_pk_add_f32 v[72:73], v[72:73], v[184:185]
	v_pk_add_f32 v[70:71], v[70:71], v[182:183]
	s_waitcnt lgkmcnt(11)
	v_pk_add_f32 v[72:73], v[72:73], v[188:189]
	v_pk_add_f32 v[70:71], v[70:71], v[186:187]
	s_waitcnt lgkmcnt(10)
	v_pk_add_f32 v[72:73], v[72:73], v[192:193]
	v_pk_add_f32 v[70:71], v[70:71], v[190:191]
	s_waitcnt lgkmcnt(9)
	v_pk_add_f32 v[72:73], v[72:73], v[196:197]
	v_pk_add_f32 v[70:71], v[70:71], v[194:195]
	s_waitcnt lgkmcnt(8)
	v_pk_add_f32 v[66:67], v[70:71], v[198:199]
	s_nop 0
	v_fmamk_f32 v66, v66, 0x3c000000, v169
	v_pk_add_f32 v[68:69], v[72:73], v[200:201]
	v_rsq_f32_e32 v66, v66
	s_nop 0
	v_mul_f32_e32 v62, v62, v66
	v_lshlrev_b32_e32 v66, 2, v97
	v_mul_lo_u32 v70, v96, s62
	v_add3_u32 v70, v115, v66, v70
	v_fmamk_f32 v66, v67, 0x3c000000, v169
	v_lshl_add_u64 v[96:97], s[96:97], 0, v[92:93]
	v_rsq_f32_e32 v66, v66
	s_nop 0
	v_mul_f32_e32 v63, v63, v66
	ds_write2_b32 v70, v62, v63 offset1:132
	v_fmamk_f32 v62, v68, 0x3c000000, v169
	v_rsq_f32_e32 v62, v62
	s_nop 0
	v_fmamk_f32 v63, v69, 0x3c000000, v169
	v_mul_f32_e32 v62, v64, v62
	s_nop 0
	v_rsq_f32_e32 v63, v63
	s_nop 0
	v_mul_f32_e32 v63, v65, v63
	v_add_u32_e32 v64, 0x400, v70
	ds_write2_b32 v64, v62, v63 offset0:8 offset1:140
	s_waitcnt lgkmcnt(8)
	v_pk_add_f32 v[68:69], v[214:215], v[218:219]
	v_pk_add_f32 v[66:67], v[212:213], v[216:217]
	s_waitcnt lgkmcnt(7)
	v_pk_add_f32 v[68:69], v[68:69], v[222:223]
	v_pk_add_f32 v[66:67], v[66:67], v[220:221]
	s_waitcnt lgkmcnt(6)
	v_pk_add_f32 v[68:69], v[68:69], v[226:227]
	v_pk_add_f32 v[66:67], v[66:67], v[224:225]
	s_waitcnt lgkmcnt(5)
	v_pk_add_f32 v[68:69], v[68:69], v[230:231]
	v_pk_add_f32 v[66:67], v[66:67], v[228:229]
	s_waitcnt lgkmcnt(4)
	v_pk_add_f32 v[68:69], v[68:69], v[234:235]
	v_pk_add_f32 v[66:67], v[66:67], v[232:233]
	s_waitcnt lgkmcnt(3)
	v_pk_add_f32 v[68:69], v[68:69], v[238:239]
	v_pk_add_f32 v[66:67], v[66:67], v[236:237]
	s_waitcnt lgkmcnt(2)
	v_pk_add_f32 v[62:63], v[66:67], v[240:241]
	s_nop 0
	v_fmamk_f32 v62, v62, 0x3c000000, v169
	v_pk_add_f32 v[64:65], v[68:69], v[242:243]
	v_rsq_f32_e32 v62, v62
	s_nop 0
	v_mul_f32_e32 v58, v58, v62
	v_fmamk_f32 v62, v63, 0x3c000000, v169
	v_rsq_f32_e32 v62, v62
	s_nop 0
	v_mul_f32_e32 v59, v59, v62
	v_add_u32_e32 v62, 0x2000, v70
	ds_write2_b32 v62, v58, v59 offset0:64 offset1:196
	v_fmamk_f32 v58, v64, 0x3c000000, v169
	v_rsq_f32_e32 v58, v58
	s_nop 0
	v_fmamk_f32 v59, v65, 0x3c000000, v169
	v_mul_f32_e32 v58, v60, v58
	s_nop 0
	v_rsq_f32_e32 v59, v59
	s_nop 0
	v_mul_f32_e32 v59, v61, v59
	v_add_u32_e32 v60, 0x2400, v70
	s_andn2_b64 vcc, exec, s[52:53]
	ds_write2_b32 v60, v58, v59 offset0:72 offset1:204
	s_cbranch_vccnz .LBB0_219
	ds_read_b128 v[58:61], v109
	ds_read_b128 v[62:65], v109 offset:16
	s_cmp_lt_u32 s22, 29
	s_cbranch_scc0 .Lrv_c1_n0
	s_waitcnt vmcnt(4)
	s_branch .Lrv_c1_end

.LBB0_227:
	s_bfe_u32 s4, s37, 0x70009
	s_mul_i32 s4, s4, 3
	s_sub_i32 s4, s36, s4
	s_and_b32 s4, s4, 0xff
	v_ashrrev_i32_e32 v58, 2, v121
	v_lshlrev_b32_e32 v83, 2, v120
	s_mul_i32 s4, s4, 0x8c00
	v_add_u32_e32 v95, v58, v83
	v_lshlrev_b32_e32 v58, 3, v121
	v_add_u32_e32 v62, s4, v168
	v_and_b32_e32 v58, 24, v58
	v_mul_lo_u32 v59, v95, s65
	v_add_u32_e32 v94, v62, v58
	v_add3_u32 v58, v94, v118, v59
	v_lshl_add_u32 v130, v120, 3, v62
	v_add_u32_e32 v62, v145, v108
	ds_read_b64_tr_b16 v[136:137], v58 offset:18432
	ds_read_b64_tr_b16 v[138:139], v58 offset:22784
	ds_read_b64_tr_b16 v[152:153], v58 offset:27136
	ds_read_b64_tr_b16 v[154:155], v58 offset:31488
	ds_read_b128 v[156:159], v62
	v_add_u32_e32 v140, s45, v121
	v_mad_u64_u32 v[160:161], s[4:5], v140, s56, v[130:131]
	ds_read2_b64 v[170:173], v160 offset1:4
	ds_read2_b64 v[174:177], v160 offset0:8 offset1:12
	v_add_u32_e32 v141, v145, v114
	ds_read_b128 v[178:181], v141 offset:1024
	ds_read_b128 v[182:185], v141
	v_add_u32_e32 v142, s43, v121
	v_mad_u64_u32 v[162:163], s[4:5], v142, s56, v[130:131]
	v_mad_u64_u32 v[186:187], s[4:5], v95, s56, v[94:95]
	ds_read2_b64 v[188:191], v162 offset1:4
	ds_read2_b64 v[192:195], v162 offset0:8 offset1:12
	ds_read_b64_tr_b16 v[196:197], v186 offset:9216
	ds_read_b64_tr_b16 v[200:201], v186 offset:9248
	ds_read_b64_tr_b16 v[198:199], v186 offset:11520
	ds_read_b64_tr_b16 v[212:213], v186 offset:13824
	ds_read_b64_tr_b16 v[214:215], v186 offset:16128
	ds_read_b64_tr_b16 v[202:203], v186 offset:11552
	ds_read_b64_tr_b16 v[216:217], v186 offset:13856
	ds_read_b64_tr_b16 v[218:219], v186 offset:16160
	ds_read_b64_tr_b16 v[220:221], v186 offset:9280
	ds_read_b64_tr_b16 v[222:223], v186 offset:11584
	ds_read_b64_tr_b16 v[224:225], v186 offset:13888
	ds_read_b64_tr_b16 v[226:227], v186 offset:16192
	ds_read_b64_tr_b16 v[228:229], v186 offset:9312
	ds_read_b64_tr_b16 v[230:231], v186 offset:11616
	ds_read_b64_tr_b16 v[232:233], v186 offset:13920
	ds_read_b64_tr_b16 v[234:235], v186 offset:16224
	s_waitcnt lgkmcnt(15)
	v_mfma_f32_16x16x32_bf16 v[62:65], v[156:159], v[136:139], v[0:3]
	v_cvt_pk_bf16_f32 v58, v50, v51
	v_cvt_pk_bf16_f32 v59, v52, v53
	v_cvt_pk_bf16_f32 v60, v38, v39
	v_cvt_pk_bf16_f32 v61, v40, v41
	v_cvt_pk_bf16_f32 v98, v42, v43
	v_cvt_pk_bf16_f32 v99, v44, v45
	v_mfma_f32_16x16x32_bf16 v[62:65], v[170:173], v[58:61], v[62:65]
	v_cvt_pk_bf16_f32 v100, v54, v55
	v_cvt_pk_bf16_f32 v101, v56, v57
	s_nop 1
	v_mfma_f32_16x16x32_bf16 v[62:65], v[174:177], v[98:101], v[62:65]
	v_mfma_f32_16x16x32_bf16 v[122:125], v[182:185], v[136:139], v[0:3]
	v_mov_b32_e32 v81, v80
	v_mfma_f32_16x16x32_bf16 v[122:125], v[178:181], v[152:155], v[122:125]
	v_pk_mul_f32 v[52:53], v[80:81], v[52:53]
	v_pk_mul_f32 v[50:51], v[84:85], v[50:51]
	v_mfma_f32_16x16x32_bf16 v[58:61], v[188:191], v[58:61], v[122:125]
	s_nop 2
	v_pk_mul_f32 v[40:41], v[80:81], v[40:41]
	v_pk_mul_f32 v[38:39], v[84:85], v[38:39]
	v_mfma_f32_16x16x32_bf16 v[58:61], v[192:195], v[98:101], v[58:61]
	v_pk_mul_f32 v[44:45], v[80:81], v[44:45]
	v_pk_mul_f32 v[42:43], v[84:85], v[42:43]
	s_waitcnt lgkmcnt(13)
	v_mfma_f32_16x16x32_bf16 v[50:53], v[196:199], v[136:139], v[50:53]
	v_pk_mul_f32 v[56:57], v[80:81], v[56:57]
	s_waitcnt lgkmcnt(11)
	v_mfma_f32_16x16x32_bf16 v[50:53], v[212:215], v[152:155], v[50:53]
	v_pk_mul_f32 v[54:55], v[84:85], v[54:55]
	v_cmp_eq_u32_e32 vcc, 0, v121
	s_waitcnt lgkmcnt(10)
	v_mfma_f32_16x16x32_bf16 v[38:41], v[200:203], v[136:139], v[38:41]
	s_waitcnt lgkmcnt(8)
	v_mfma_f32_16x16x32_bf16 v[38:41], v[216:219], v[152:155], v[38:41]
	s_waitcnt lgkmcnt(6)
	v_mfma_f32_16x16x32_bf16 v[42:45], v[220:223], v[136:139], v[42:45]
	s_waitcnt lgkmcnt(4)
	v_mfma_f32_16x16x32_bf16 v[42:45], v[224:227], v[152:155], v[42:45]
	s_waitcnt lgkmcnt(2)
	v_mfma_f32_16x16x32_bf16 v[54:57], v[228:231], v[136:139], v[54:57]
	s_waitcnt lgkmcnt(0)
	v_mfma_f32_16x16x32_bf16 v[54:57], v[232:235], v[152:155], v[54:57]
	v_mul_f32_e32 v170, v62, v62
	v_mul_f32_e32 v171, v63, v63
	v_mul_f32_e32 v172, v64, v64
	v_mul_f32_e32 v173, v65, v65
	v_mul_f32_e32 v174, v58, v58
	v_mul_f32_e32 v175, v59, v59
	v_mul_f32_e32 v176, v60, v60
	v_mul_f32_e32 v177, v61, v61
	v_add_u32_e32 v66, v83, v112
	v_lshl_add_u32 v66, v66, 2, v147
	v_mov_b32_dpp v178, v170 quad_perm:[1,0,3,2] row_mask:0xf bank_mask:0xf
	v_mov_b32_dpp v179, v171 quad_perm:[1,0,3,2] row_mask:0xf bank_mask:0xf
	v_mov_b32_dpp v180, v172 quad_perm:[1,0,3,2] row_mask:0xf bank_mask:0xf
	v_mov_b32_dpp v181, v173 quad_perm:[1,0,3,2] row_mask:0xf bank_mask:0xf
	v_mov_b32_dpp v182, v174 quad_perm:[1,0,3,2] row_mask:0xf bank_mask:0xf
	v_mov_b32_dpp v183, v175 quad_perm:[1,0,3,2] row_mask:0xf bank_mask:0xf
	v_mov_b32_dpp v184, v176 quad_perm:[1,0,3,2] row_mask:0xf bank_mask:0xf
	v_mov_b32_dpp v185, v177 quad_perm:[1,0,3,2] row_mask:0xf bank_mask:0xf
	v_fmac_f32_e32 v178, v62, v62
	v_fmac_f32_e32 v179, v63, v63
	v_fmac_f32_e32 v180, v64, v64
	v_fmac_f32_e32 v181, v65, v65
	v_fmac_f32_e32 v182, v58, v58
	v_fmac_f32_e32 v183, v59, v59
	v_fmac_f32_e32 v184, v60, v60
	v_fmac_f32_e32 v185, v61, v61
	v_add_f32_dpp v170, v178, v178 quad_perm:[2,3,0,1] row_mask:0xf bank_mask:0xf bound_ctrl:1
	v_add_f32_dpp v171, v179, v179 quad_perm:[2,3,0,1] row_mask:0xf bank_mask:0xf bound_ctrl:1
	v_add_f32_dpp v172, v180, v180 quad_perm:[2,3,0,1] row_mask:0xf bank_mask:0xf bound_ctrl:1
	v_add_f32_dpp v173, v181, v181 quad_perm:[2,3,0,1] row_mask:0xf bank_mask:0xf bound_ctrl:1
	v_add_f32_dpp v174, v182, v182 quad_perm:[2,3,0,1] row_mask:0xf bank_mask:0xf bound_ctrl:1
	v_add_f32_dpp v175, v183, v183 quad_perm:[2,3,0,1] row_mask:0xf bank_mask:0xf bound_ctrl:1
	v_add_f32_dpp v176, v184, v184 quad_perm:[2,3,0,1] row_mask:0xf bank_mask:0xf bound_ctrl:1
	v_add_f32_dpp v177, v185, v185 quad_perm:[2,3,0,1] row_mask:0xf bank_mask:0xf bound_ctrl:1
	v_add_f32_dpp v170, v170, v170 row_half_mirror row_mask:0xf bank_mask:0xf bound_ctrl:1
	v_add_f32_dpp v171, v171, v171 row_half_mirror row_mask:0xf bank_mask:0xf bound_ctrl:1
	v_add_f32_dpp v172, v172, v172 row_half_mirror row_mask:0xf bank_mask:0xf bound_ctrl:1
	v_add_f32_dpp v173, v173, v173 row_half_mirror row_mask:0xf bank_mask:0xf bound_ctrl:1
	v_add_f32_dpp v174, v174, v174 row_half_mirror row_mask:0xf bank_mask:0xf bound_ctrl:1
	v_add_f32_dpp v175, v175, v175 row_half_mirror row_mask:0xf bank_mask:0xf bound_ctrl:1
	v_add_f32_dpp v176, v176, v176 row_half_mirror row_mask:0xf bank_mask:0xf bound_ctrl:1
	v_add_f32_dpp v177, v177, v177 row_half_mirror row_mask:0xf bank_mask:0xf bound_ctrl:1
	v_mov_b32_dpp v178, v170 row_mirror row_mask:0xf bank_mask:0xf
	v_mov_b32_dpp v179, v171 row_mirror row_mask:0xf bank_mask:0xf
	v_mov_b32_dpp v180, v172 row_mirror row_mask:0xf bank_mask:0xf
	v_mov_b32_dpp v181, v173 row_mirror row_mask:0xf bank_mask:0xf
	v_mov_b32_dpp v182, v174 row_mirror row_mask:0xf bank_mask:0xf
	v_mov_b32_dpp v183, v175 row_mirror row_mask:0xf bank_mask:0xf
	v_mov_b32_dpp v184, v176 row_mirror row_mask:0xf bank_mask:0xf
	v_mov_b32_dpp v185, v177 row_mirror row_mask:0xf bank_mask:0xf
	s_and_saveexec_b64 s[4:5], vcc
	v_add_f32_e32 v170, v170, v178
	v_add_f32_e32 v171, v171, v179
	v_add_f32_e32 v172, v172, v180
	v_add_f32_e32 v173, v173, v181
	v_add_f32_e32 v174, v174, v182
	v_add_f32_e32 v175, v175, v183
	v_add_f32_e32 v176, v176, v184
	v_add_f32_e32 v177, v177, v185
	ds_write_b32 v66, v170
	ds_write_b32 v66, v171 offset:4
	ds_write_b32 v66, v172 offset:8
	ds_write_b32 v66, v173 offset:12
	ds_write_b32 v66, v174 offset:64
	ds_write_b32 v66, v175 offset:68
	ds_write_b32 v66, v176 offset:72
	ds_write_b32 v66, v177 offset:76
	s_or_b64 exec, exec, s[4:5]
	s_andn2_b64 vcc, exec, s[46:47]
	s_cbranch_vccnz .LBB0_190
	s_add_i32 s4, s22, 3
	s_and_b32 s5, s4, 0xff
	s_mulk_i32 s5, 0xab
	s_bfe_u32 s5, s5, 0x70009
	s_mul_i32 s5, s5, 3
	s_sub_i32 s4, s4, s5
	s_and_b32 s4, s4, 0xff
	s_mul_i32 s4, s4, 0x8c00
	v_add_u32_e32 v66, s4, v76
	v_lshl_add_u32 v67, v106, 1, v66
	v_add3_u32 v66, v66, v77, v119
	s_cmp_eq_u32 s22, 28
	s_cbranch_scc0 .Lrv_b2_n0
	s_waitcnt vmcnt(2)
	s_branch .Lrv_b2_end
